# nt on the dilated-combine loads (dead after read) + longer sleep between group-barrier polls
# baseline (speedup 1.0000x reference)
; DI unsigned xb_ld(unsigned* p)              { return __hip_atomic_load(p, __ATOMIC_RELAXED, __HIP_MEMORY_SCOPE_AGENT); }
; DI unsigned xb_add(unsigned* p, unsigned v) { return __hip_atomic_fetch_add(p, v, __ATOMIC_RELAXED, __HIP_MEMORY_SCOPE_AGENT); }
; #define XB_SPIN(cond, bar) do { unsigned _sp = 0; while (cond) { __builtin_amdgcn_s_sleep(1); \
;     if ((++_sp & 255u) == 0u) { if (xb_ld(&(bar)[XB_TMO])) break; if (_sp > XB_SPIN_CAP) { atomicAdd(&(bar)[XB_TMO], 1u); break; } } } } while (0)
; DI void xcd_barrier(const XcdBarrier& b) {
;     ...
;               else XB_SPIN(xb_ld(&bar[XB_TOPGEN]) == tg, bar);
;             }
;             __builtin_amdgcn_fence(__ATOMIC_ACQUIRE, "agent");
;             xb_add(&bar[XB_XGEN(b.x)], 1u);
;             asm volatile("s_waitcnt vmcnt(0)" ::: "memory");
;         } else {
;             XB_SPIN(xb_ld(&bar[XB_XGEN(b.x)]) == gen, bar);
.LBB0_186:
	s_and_b32 s12, s16, 0xff
	s_mov_b64 s[10:11], -1
	s_cmp_lg_u32 s12, 0
	s_mov_b64 s[14:15], -1
	s_sleep 6
	s_cbranch_scc0 .LBB0_189
	s_and_b64 vcc, exec, s[14:15]
	s_cbranch_vccz .LBB0_185

; #define MFMA(a, b, c) __builtin_amdgcn_mfma_f32_32x32x16_bf16((a), (b), (c), 0, 0, 0)
; DI float bf2f(u16 v) { return __uint_as_float((unsigned)v << 16); }
; DI u16 f2bf(float x) { return (u16)(pk2(x, 0.f) & 0xffffu); }
; DI float lo16(unsigned w) { return __uint_as_float(w << 16); }
; DI float hi16(unsigned w) { return __uint_as_float(w & 0xffff0000u); }
; DI float siluf_(float x) { return x / (1.f + __expf(-x)); }
; DI void pool_item(const Params& p, int l, int it, char* lds) {
;     ...
;     const int ch = tid, w = 2 << g;
;     float s = 0.f;
;     for (int r = 17 - w; r <= 16; ++r) s += bf2f(cin[r * 256 + ch]);
; #pragma unroll 4
;     for (int i = 0; i < 32; ++i) {
;       const int t = q0 + i; const int cnt = (t + 1 < w) ? t + 1 : w;
;       const float self = bf2f(cin[(i + 16) * 256 + ch]);
;       *(u16*)(pl + i * 528 + ch * 2) = f2bf(s / (float)cnt - self);
;       s += bf2f(cin[(i + 17) * 256 + ch]) - bf2f(cin[(i + 17 - w) * 256 + ch]);
;     }
;   }
;   __syncthreads();
;   f32x16 acc[2];
; #pragma unroll
;   for (int r = 0; r < 16; ++r) { acc[0][r] = 0.f; acc[1][r] = 0.f; }
; #pragma unroll
;   for (int s4 = 0; s4 < 4; ++s4) {
;     const bf16x8 bf = *(const bf16x8*)(pl + l31 * 528 + (g * 64 + 16 * s4 + 8 * hi) * 2);
; #pragma unroll
;     for (int dt = 0; dt < 2; ++dt) acc[dt] = MFMA(af[s4 * 2 + dt], bf, acc[dt]);
;   }
;   u16* y = (u16*)(ws_ + OFF_XB);
; #pragma unroll
;   for (int dt = 0; dt < 2; ++dt)
; #pragma unroll
;     for (int g4 = 0; g4 < 4; ++g4) {
;       const int col = g * 64 + dt * 32 + 8 * g4 + 4 * hi;
;       const f32x4 ps = psv[dt * 4 + g4];
;       const u32x2 z = zv[dt * 4 + g4];
;       u32x2 v;
;       v[0] = pk2(acc[dt][4 * g4] * ps[0] * siluf_(lo16(z[0])), acc[dt][4 * g4 + 1] * ps[1] * siluf_(hi16(z[0])));
;       v[1] = pk2(acc[dt][4 * g4 + 2] * ps[2] * siluf_(lo16(z[1])), acc[dt][4 * g4 + 3] * ps[3] * siluf_(hi16(z[1])));
;       *(u32x2*)(y + tok * 1024 + 512 + col) = v;
;     }
.LBB0_464:
	v_add_u32_e32 v15, s2, v118
	v_add_u32_e32 v16, 1, v15
	v_min_i32_e32 v16, v16, v9
	v_cvt_f32_i32_e32 v16, v16
	s_waitcnt lgkmcnt(0)
	v_lshlrev_b32_e32 v14, 16, v14
	s_add_i32 s2, s2, 4
	s_cmp_lg_u32 s2, 32
	s_nop 0
	v_rcp_f32_e32 v16, v16
	s_nop 0
	v_mul_f32_e32 v16, v12, v16
	v_sub_f32_e32 v14, v16, v14
	v_cvt_pk_bf16_f32 v14, v14, s0
	ds_write_b16 v11, v14
	v_add_u32_e32 v16, v13, v10
	ds_read_u16 v14, v16 offset:512
	ds_read_u16 v17, v13 offset:512
	s_waitcnt lgkmcnt(1)
	v_lshlrev_b32_e32 v14, 16, v14
	s_waitcnt lgkmcnt(0)
	v_lshlrev_b32_e32 v17, 16, v17
	v_sub_f32_e32 v14, v17, v14
	v_add_f32_e32 v12, v12, v14
	v_add_u32_e32 v14, 2, v15
	v_min_i32_e32 v14, v14, v9
	v_cvt_f32_i32_e32 v14, v14
	s_nop 0
	v_rcp_f32_e32 v14, v14
	s_nop 0
	v_mul_f32_e32 v14, v12, v14
	v_sub_f32_e32 v14, v14, v17
	v_cvt_pk_bf16_f32 v14, v14, s0
	ds_write_b16 v11, v14 offset:528
	ds_read_u16 v14, v16 offset:1024
	ds_read_u16 v17, v13 offset:1024
	s_waitcnt lgkmcnt(1)
	v_lshlrev_b32_e32 v14, 16, v14
	s_waitcnt lgkmcnt(0)
	v_lshlrev_b32_e32 v17, 16, v17
	v_sub_f32_e32 v14, v17, v14
	v_add_f32_e32 v12, v12, v14
	v_add_u32_e32 v14, 3, v15
	v_min_i32_e32 v14, v14, v9
	v_cvt_f32_i32_e32 v14, v14
	s_nop 0
	v_rcp_f32_e32 v14, v14
	s_nop 0
	v_mul_f32_e32 v14, v12, v14
	v_sub_f32_e32 v14, v14, v17
	v_cvt_pk_bf16_f32 v14, v14, s0
	ds_write_b16 v11, v14 offset:1056
	ds_read_u16 v14, v16 offset:1536
	ds_read_u16 v17, v13 offset:1536
	s_waitcnt lgkmcnt(1)
	v_lshlrev_b32_e32 v14, 16, v14
	s_waitcnt lgkmcnt(0)
	v_lshlrev_b32_e32 v17, 16, v17
	v_sub_f32_e32 v14, v17, v14
	v_add_f32_e32 v12, v12, v14
	v_add_u32_e32 v14, 4, v15
	v_min_i32_e32 v14, v14, v9
	v_cvt_f32_i32_e32 v14, v14
	s_nop 0
	v_rcp_f32_e32 v14, v14
	s_nop 0
	v_mul_f32_e32 v14, v12, v14
	v_sub_f32_e32 v14, v14, v17
	v_cvt_pk_bf16_f32 v14, v14, s0
	ds_write_b16 v11, v14 offset:1584
	v_add_u32_e32 v15, 0x800, v13
	ds_read_u16 v14, v13 offset:2048
	ds_read_u16 v13, v16 offset:2048
	v_add_u32_e32 v11, 0x840, v11
	s_waitcnt lgkmcnt(1)
	v_lshlrev_b32_e32 v16, 16, v14
	s_waitcnt lgkmcnt(0)
	v_lshlrev_b32_e32 v13, 16, v13
	v_sub_f32_e32 v13, v16, v13
	v_add_f32_e32 v12, v12, v13
	v_mov_b32_e32 v13, v15
	s_cbranch_scc1 .LBB0_464
	v_mul_u32_u24_e32 v9, 0x210, v120
	v_and_b32_e32 v8, 0xffffff80, v8
	v_add3_u32 v124, v9, v178, v8
	s_barrier
	ds_read_b128 v[8:11], v124 offset:24576
	ds_read_b128 v[120:123], v124 offset:24608
	s_waitcnt vmcnt(23) lgkmcnt(1)
	v_mfma_f32_32x32x16_bf16 v[16:31], v[0:3], v[8:11], 0
	v_mov_b32_e32 v183, v179
	s_mov_b64 s[2:3], 0xd390000
	v_mov_b32_e32 v185, v179
	s_mov_b64 s[4:5], 0x8000
	v_add_u32_e32 v118, 32, v118
	s_waitcnt vmcnt(22)
	v_mfma_f32_32x32x16_bf16 v[0:15], v[4:7], v[8:11], 0
	s_waitcnt vmcnt(21) lgkmcnt(0)
	v_mfma_f32_32x32x16_bf16 v[16:31], v[76:79], v[120:123], v[16:31]
	ds_read_b128 v[76:79], v124 offset:24640
	s_waitcnt vmcnt(19)
	v_mfma_f32_32x32x16_bf16 v[0:15], v[84:87], v[120:123], v[0:15]
	s_waitcnt lgkmcnt(0)
	v_mfma_f32_32x32x16_bf16 v[16:31], v[64:67], v[76:79], v[16:31]
	ds_read_b128 v[64:67], v124 offset:24672
	s_waitcnt vmcnt(18)
	v_mfma_f32_32x32x16_bf16 v[0:15], v[80:83], v[76:79], v[0:15]
	s_waitcnt vmcnt(17) lgkmcnt(0)
	v_mfma_f32_32x32x16_bf16 v[16:31], v[68:71], v[64:67], v[16:31]
	s_waitcnt vmcnt(11)
	v_lshlrev_b32_e32 v68, 16, v112
	v_and_b32_e32 v69, 0xffff0000, v112
	v_mfma_f32_32x32x16_bf16 v[0:15], v[72:75], v[64:67], v[0:15]
	v_mul_f32_e32 v66, 0xbfb8aa3b, v68
	s_nop 6
	v_mul_f32_e64 v16, v60, v16
	v_mul_f32_e64 v17, v61, v17
	v_mul_f32_e32 v60, 0xbfb8aa3b, v69
	v_exp_f32_e32 v66, v66
	v_exp_f32_e32 v67, v60
	v_lshlrev_b64 v[64:65], 11, v[114:115]
	v_lshl_add_u64 v[64:65], s[0:1], 0, v[64:65]
	s_mov_b64 s[0:1], 0x2a40400
	v_pk_add_f32 v[60:61], v[66:67], 1.0 op_sel_hi:[1,0]
	v_lshl_add_u64 v[64:65], v[64:65], 0, s[0:1]
	v_pk_mul_f32 v[18:19], v[62:63], v[18:19]
	v_pk_mul_f32 v[20:21], v[56:57], v[20:21]
	v_pk_mul_f32 v[22:23], v[58:59], v[22:23]
	v_rcp_f32_e32 v61, v61
	s_nop 0
	v_mul_f32_e32 v61, v69, v61
	s_waitcnt vmcnt(7)
	v_pk_mul_f32 v[0:1], v[44:45], v[0:1]
	v_pk_mul_f32 v[2:3], v[46:47], v[2:3]
	v_rcp_f32_e32 v60, v60
	s_nop 0
	v_mul_f32_e32 v60, v68, v60
	v_pk_mul_f32 v[16:17], v[60:61], v[16:17]
	v_lshlrev_b32_e32 v61, 16, v113
	v_and_b32_e32 v66, 0xffff0000, v113
	v_cvt_pk_bf16_f32 v60, v16, v17
	v_mul_f32_e32 v16, 0xbfb8aa3b, v61
	v_mul_f32_e32 v17, 0xbfb8aa3b, v66
	v_exp_f32_e32 v16, v16
	v_exp_f32_e32 v17, v17
	s_nop 0
	v_pk_add_f32 v[16:17], v[16:17], 1.0 op_sel_hi:[1,0]
	s_nop 0
	s_nop 0
	v_rcp_f32_e32 v17, v17
	s_nop 0
	v_mul_f32_e32 v17, v66, v17
	s_nop 0
	v_rcp_f32_e32 v16, v16
	s_nop 0
	v_mul_f32_e32 v16, v61, v16
	v_pk_mul_f32 v[16:17], v[16:17], v[18:19]
	s_nop 0
	v_cvt_pk_bf16_f32 v61, v16, v17
	v_lshl_add_u64 v[16:17], v[110:111], 1, v[64:65]
	global_store_dwordx2 v[16:17], v[60:61], off
	v_lshlrev_b32_e32 v60, 16, v108
	v_and_b32_e32 v61, 0xffff0000, v108
	v_mul_f32_e32 v18, 0xbfb8aa3b, v60
	v_mul_f32_e32 v19, 0xbfb8aa3b, v61
	v_exp_f32_e32 v18, v18
	v_exp_f32_e32 v19, v19
	s_nop 0
	v_pk_add_f32 v[18:19], v[18:19], 1.0 op_sel_hi:[1,0]
	s_nop 0
	s_nop 0
	v_rcp_f32_e32 v19, v19
	s_nop 0
	v_mul_f32_e32 v19, v61, v19
	s_nop 0
	v_rcp_f32_e32 v18, v18
	s_nop 0
	v_mul_f32_e32 v18, v60, v18
	v_pk_mul_f32 v[18:19], v[18:19], v[20:21]
	v_and_b32_e32 v56, 0xffff0000, v109
	v_cvt_pk_bf16_f32 v18, v18, v19
	v_lshlrev_b32_e32 v19, 16, v109
	v_mul_f32_e32 v20, 0xbfb8aa3b, v19
	v_mul_f32_e32 v21, 0xbfb8aa3b, v56
	v_exp_f32_e32 v20, v20
	v_exp_f32_e32 v21, v21
	s_nop 0
	v_pk_add_f32 v[20:21], v[20:21], 1.0 op_sel_hi:[1,0]
	s_nop 0
	s_nop 0
	v_rcp_f32_e32 v21, v21
	s_nop 0
	v_mul_f32_e32 v21, v56, v21
	s_nop 0
	v_rcp_f32_e32 v20, v20
; DI float lo16(unsigned w) { return __uint_as_float(w << 16); }
; DI float hi16(unsigned w) { return __uint_as_float(w & 0xffff0000u); }
; DI float siluf_(float x) { return x / (1.f + __expf(-x)); }
; DI void pool_item(const Params& p, int l, int it, char* lds) {
;     ...
; #pragma unroll
;   for (int dt = 0; dt < 2; ++dt)
; #pragma unroll
;     for (int g4 = 0; g4 < 4; ++g4) {
;       const int col = g * 64 + dt * 32 + 8 * g4 + 4 * hi;
;       const f32x4 ps = psv[dt * 4 + g4];
;       const u32x2 z = zv[dt * 4 + g4];
;       u32x2 v;
;       v[0] = pk2(acc[dt][4 * g4] * ps[0] * siluf_(lo16(z[0])), acc[dt][4 * g4 + 1] * ps[1] * siluf_(hi16(z[0])));
;       v[1] = pk2(acc[dt][4 * g4 + 2] * ps[2] * siluf_(lo16(z[1])), acc[dt][4 * g4 + 3] * ps[3] * siluf_(hi16(z[1])));
;       *(u32x2*)(y + tok * 1024 + 512 + col) = v;
;     }
	s_nop 0
	v_mul_f32_e32 v20, v19, v20
	v_pk_mul_f32 v[20:21], v[20:21], v[22:23]
	v_lshlrev_b32_e32 v22, 16, v104
	v_cvt_pk_bf16_f32 v19, v20, v21
	v_lshl_add_u64 v[20:21], v[106:107], 1, v[64:65]
	v_and_b32_e32 v23, 0xffff0000, v104
	global_store_dwordx2 v[20:21], v[18:19], off
	v_mul_f32_e32 v18, 0xbfb8aa3b, v22
	v_mul_f32_e32 v19, 0xbfb8aa3b, v23
	v_exp_f32_e32 v18, v18
	v_exp_f32_e32 v19, v19
	v_pk_mul_f32 v[20:21], v[52:53], v[24:25]
	v_pk_add_f32 v[18:19], v[18:19], 1.0 op_sel_hi:[1,0]
	s_nop 0
	s_nop 0
	v_rcp_f32_e32 v19, v19
	s_nop 0
	v_mul_f32_e32 v19, v23, v19
	s_nop 0
	v_rcp_f32_e32 v18, v18
	s_nop 0
	v_mul_f32_e32 v18, v22, v18
	v_pk_mul_f32 v[18:19], v[18:19], v[20:21]
	v_and_b32_e32 v24, 0xffff0000, v105
	v_cvt_pk_bf16_f32 v18, v18, v19
	v_lshlrev_b32_e32 v19, 16, v105
	v_mul_f32_e32 v20, 0xbfb8aa3b, v19
	v_mul_f32_e32 v21, 0xbfb8aa3b, v24
	v_exp_f32_e32 v20, v20
	v_exp_f32_e32 v21, v21
	v_pk_mul_f32 v[22:23], v[54:55], v[26:27]
	v_pk_add_f32 v[20:21], v[20:21], 1.0 op_sel_hi:[1,0]
	s_nop 0
	s_nop 0
	v_rcp_f32_e32 v21, v21
	s_nop 0
	v_mul_f32_e32 v21, v24, v21
	s_nop 0
	v_rcp_f32_e32 v20, v20
	s_nop 0
	v_mul_f32_e32 v20, v19, v20
	v_pk_mul_f32 v[20:21], v[20:21], v[22:23]
	v_lshlrev_b32_e32 v22, 16, v100
	v_cvt_pk_bf16_f32 v19, v20, v21
	v_lshl_add_u64 v[20:21], v[102:103], 1, v[64:65]
	v_and_b32_e32 v23, 0xffff0000, v100
	global_store_dwordx2 v[20:21], v[18:19], off
	v_mul_f32_e32 v18, 0xbfb8aa3b, v22
	v_mul_f32_e32 v19, 0xbfb8aa3b, v23
	v_exp_f32_e32 v18, v18
	v_exp_f32_e32 v19, v19
	v_pk_mul_f32 v[20:21], v[48:49], v[28:29]
	v_pk_add_f32 v[18:19], v[18:19], 1.0 op_sel_hi:[1,0]
	s_nop 0
	s_nop 0
	v_rcp_f32_e32 v19, v19
	s_nop 0
	v_mul_f32_e32 v19, v23, v19
	s_nop 0
	v_rcp_f32_e32 v18, v18
	s_nop 0
	v_mul_f32_e32 v18, v22, v18
	v_pk_mul_f32 v[18:19], v[18:19], v[20:21]
	v_and_b32_e32 v24, 0xffff0000, v101
	v_cvt_pk_bf16_f32 v18, v18, v19
	v_lshlrev_b32_e32 v19, 16, v101
	v_mul_f32_e32 v20, 0xbfb8aa3b, v19
	v_mul_f32_e32 v21, 0xbfb8aa3b, v24
	v_exp_f32_e32 v20, v20
	v_exp_f32_e32 v21, v21
	v_pk_mul_f32 v[22:23], v[50:51], v[30:31]
	v_pk_add_f32 v[20:21], v[20:21], 1.0 op_sel_hi:[1,0]
	s_nop 0
	s_nop 0
	v_rcp_f32_e32 v21, v21
	s_nop 0
	v_mul_f32_e32 v21, v24, v21
	s_nop 0
	v_rcp_f32_e32 v20, v20
	s_nop 0
	v_mul_f32_e32 v20, v19, v20
	v_pk_mul_f32 v[20:21], v[20:21], v[22:23]
	s_nop 0
	v_cvt_pk_bf16_f32 v19, v20, v21
	v_lshl_add_u64 v[20:21], v[98:99], 1, v[64:65]
	global_store_dwordx2 v[20:21], v[18:19], off
	s_waitcnt vmcnt(7)
	v_lshlrev_b32_e32 v20, 16, v96
	v_and_b32_e32 v21, 0xffff0000, v96
	v_mul_f32_e32 v18, 0xbfb8aa3b, v20
	v_mul_f32_e32 v19, 0xbfb8aa3b, v21
	v_exp_f32_e32 v18, v18
	v_exp_f32_e32 v19, v19
	s_nop 0
	v_pk_add_f32 v[18:19], v[18:19], 1.0 op_sel_hi:[1,0]
	s_nop 0
	s_nop 0
	v_rcp_f32_e32 v19, v19
	s_nop 0
	v_mul_f32_e32 v19, v21, v19
	s_nop 0
	v_rcp_f32_e32 v18, v18
	s_nop 0
	v_mul_f32_e32 v18, v20, v18
	v_pk_mul_f32 v[0:1], v[18:19], v[0:1]
	v_and_b32_e32 v20, 0xffff0000, v97
	v_cvt_pk_bf16_f32 v0, v0, v1
	v_lshlrev_b32_e32 v1, 16, v97
	v_mul_f32_e32 v18, 0xbfb8aa3b, v1
	v_mul_f32_e32 v19, 0xbfb8aa3b, v20
	v_exp_f32_e32 v18, v18
	v_exp_f32_e32 v19, v19
	s_nop 0
	v_pk_add_f32 v[18:19], v[18:19], 1.0 op_sel_hi:[1,0]
	s_nop 0
	s_nop 0
	v_rcp_f32_e32 v19, v19
	s_nop 0
	v_mul_f32_e32 v19, v20, v19
	s_nop 0
	v_rcp_f32_e32 v18, v18
	s_nop 0
	v_mul_f32_e32 v18, v1, v18
	v_pk_mul_f32 v[2:3], v[18:19], v[2:3]
	s_waitcnt vmcnt(6)
	v_lshlrev_b32_e32 v18, 16, v92
	v_cvt_pk_bf16_f32 v1, v2, v3
	v_lshl_add_u64 v[2:3], v[94:95], 1, v[64:65]
	v_and_b32_e32 v19, 0xffff0000, v92
	global_store_dwordx2 v[2:3], v[0:1], off
	v_mul_f32_e32 v0, 0xbfb8aa3b, v18
	v_mul_f32_e32 v1, 0xbfb8aa3b, v19
	v_exp_f32_e32 v0, v0
	v_exp_f32_e32 v1, v1
	v_pk_mul_f32 v[2:3], v[40:41], v[4:5]
	v_pk_add_f32 v[0:1], v[0:1], 1.0 op_sel_hi:[1,0]
	s_nop 0
	s_nop 0
	v_rcp_f32_e32 v1, v1
	s_nop 0
	v_mul_f32_e32 v1, v19, v1
	s_nop 0
	v_rcp_f32_e32 v0, v0
	s_nop 0
	v_mul_f32_e32 v0, v18, v0
	v_pk_mul_f32 v[0:1], v[0:1], v[2:3]
	v_and_b32_e32 v18, 0xffff0000, v93
	v_cvt_pk_bf16_f32 v0, v0, v1
	v_lshlrev_b32_e32 v1, 16, v93
	v_mul_f32_e32 v2, 0xbfb8aa3b, v1
	v_mul_f32_e32 v3, 0xbfb8aa3b, v18
	v_exp_f32_e32 v2, v2
	v_exp_f32_e32 v3, v3
	v_pk_mul_f32 v[4:5], v[42:43], v[6:7]
	v_pk_add_f32 v[2:3], v[2:3], 1.0 op_sel_hi:[1,0]
	s_nop 0
	s_nop 0
	v_rcp_f32_e32 v3, v3
	s_nop 0
	v_mul_f32_e32 v3, v18, v3
	s_nop 0
	v_rcp_f32_e32 v2, v2
	s_nop 0
	v_mul_f32_e32 v2, v1, v2
	v_pk_mul_f32 v[2:3], v[2:3], v[4:5]
	s_waitcnt vmcnt(6)
	v_lshlrev_b32_e32 v4, 16, v90
	v_cvt_pk_bf16_f32 v1, v2, v3
	v_and_b32_e32 v5, 0xffff0000, v90
	global_store_dwordx2 v[16:17], v[0:1], off offset:80
	v_mul_f32_e32 v0, 0xbfb8aa3b, v4
	v_mul_f32_e32 v1, 0xbfb8aa3b, v5
	v_exp_f32_e32 v0, v0
	v_exp_f32_e32 v1, v1
	v_pk_mul_f32 v[2:3], v[36:37], v[8:9]
	v_pk_add_f32 v[0:1], v[0:1], 1.0 op_sel_hi:[1,0]
	s_nop 0
	s_nop 0
	v_rcp_f32_e32 v1, v1
	s_nop 0
	v_mul_f32_e32 v1, v5, v1
	s_nop 0
	v_rcp_f32_e32 v0, v0
	s_nop 0
	v_mul_f32_e32 v0, v4, v0
	v_pk_mul_f32 v[0:1], v[0:1], v[2:3]
	v_and_b32_e32 v6, 0xffff0000, v91
	v_cvt_pk_bf16_f32 v0, v0, v1
	v_lshlrev_b32_e32 v1, 16, v91
	v_mul_f32_e32 v2, 0xbfb8aa3b, v1
	v_mul_f32_e32 v3, 0xbfb8aa3b, v6
	v_exp_f32_e32 v2, v2
	v_exp_f32_e32 v3, v3
	v_pk_mul_f32 v[4:5], v[38:39], v[10:11]
	v_pk_add_f32 v[2:3], v[2:3], 1.0 op_sel_hi:[1,0]
	s_nop 0
	s_nop 0
	v_rcp_f32_e32 v3, v3
	s_nop 0
	v_mul_f32_e32 v3, v6, v3
	s_nop 0
	v_rcp_f32_e32 v2, v2
	s_nop 0
	v_mul_f32_e32 v2, v1, v2
	v_pk_mul_f32 v[2:3], v[2:3], v[4:5]
	s_waitcnt vmcnt(6)
; DI float lo16(unsigned w) { return __uint_as_float(w << 16); }
; DI float hi16(unsigned w) { return __uint_as_float(w & 0xffff0000u); }
; DI float siluf_(float x) { return x / (1.f + __expf(-x)); }
; DI void pool_item(const Params& p, int l, int it, char* lds) {
;     ...
;       v[0] = pk2(acc[dt][4 * g4] * ps[0] * siluf_(lo16(z[0])), acc[dt][4 * g4 + 1] * ps[1] * siluf_(hi16(z[0])));
;       v[1] = pk2(acc[dt][4 * g4 + 2] * ps[2] * siluf_(lo16(z[1])), acc[dt][4 * g4 + 3] * ps[3] * siluf_(hi16(z[1])));
;       *(u32x2*)(y + tok * 1024 + 512 + col) = v;
; DI void dilcomb_item(const Params& p, int it) {
;     ...
;   for (int i = 0; i < 4; ++i) {
;     const int idx = it * 1024 + i * 256 + threadIdx.x;
;     const size_t tok = idx >> 5; const int c8 = idx & 31, h = c8 >> 3;
;     const float l0 = lse[((size_t)0 * T_ + tok) * 4 + h], l1 = lse[((size_t)1 * T_ + tok) * 4 + h], l2 = lse[((size_t)2 * T_ + tok) * 4 + h];
;     const float mx = fmaxf(l0, fmaxf(l1, l2));
;     float w0 = __expf(l0 - mx), w1 = __expf(l1 - mx), w2 = __expf(l2 - mx);
;     const float iw = 1.f / (w0 + w1 + w2); w0 *= iw; w1 *= iw; w2 *= iw;
;     const u32x4 a = *(const u32x4*)(od + ((size_t)0 * T_ + tok) * 256 + c8 * 8), bq = *(const u32x4*)(od + ((size_t)1 * T_ + tok) * 256 + c8 * 8), cq = *(const u32x4*)(od + ((size_t)2 * T_ + tok) * 256 + c8 * 8);
;     const u32x4 z = *(const u32x4*)(proj + tok * NP + C_BZ + c8 * 8);
	v_lshlrev_b32_e32 v4, 16, v88
	v_cvt_pk_bf16_f32 v1, v2, v3
	v_and_b32_e32 v5, 0xffff0000, v88
	global_store_dwordx2 v[16:17], v[0:1], off offset:96
	v_mul_f32_e32 v0, 0xbfb8aa3b, v4
	v_mul_f32_e32 v1, 0xbfb8aa3b, v5
	v_exp_f32_e32 v0, v0
	v_exp_f32_e32 v1, v1
	v_pk_mul_f32 v[2:3], v[32:33], v[12:13]
	v_pk_add_f32 v[0:1], v[0:1], 1.0 op_sel_hi:[1,0]
	s_nop 0
	s_nop 0
	v_rcp_f32_e32 v1, v1
	s_nop 0
	v_mul_f32_e32 v1, v5, v1
	s_nop 0
	v_rcp_f32_e32 v0, v0
	s_nop 0
	v_mul_f32_e32 v0, v4, v0
	v_pk_mul_f32 v[0:1], v[0:1], v[2:3]
	v_and_b32_e32 v6, 0xffff0000, v89
	v_cvt_pk_bf16_f32 v0, v0, v1
	v_lshlrev_b32_e32 v1, 16, v89
	v_mul_f32_e32 v2, 0xbfb8aa3b, v1
	v_mul_f32_e32 v3, 0xbfb8aa3b, v6
	v_exp_f32_e32 v2, v2
	v_exp_f32_e32 v3, v3
	v_pk_mul_f32 v[4:5], v[34:35], v[14:15]
	v_pk_add_f32 v[2:3], v[2:3], 1.0 op_sel_hi:[1,0]
	s_nop 0
	s_nop 0
	v_rcp_f32_e32 v3, v3
	s_nop 0
	v_mul_f32_e32 v3, v6, v3
	s_mov_b64 s[0:1], 0
	v_rcp_f32_e32 v2, v2
	s_nop 0
	v_mul_f32_e32 v2, v1, v2
	v_pk_mul_f32 v[2:3], v[2:3], v[4:5]
	s_nop 0
	v_cvt_pk_bf16_f32 v1, v2, v3
	global_store_dwordx2 v[16:17], v[0:1], off offset:112
	v_add_u32_e32 v0, s14, v119
	s_add_u32 s0, s90, s0
	s_addc_u32 s1, s91, s1
	v_lshl_or_b32 v31, v0, 10, v176
	v_lshl_add_u64 v[0:1], s[0:1], 0, v[182:183]
	v_ashrrev_i32_e32 v12, 5, v31
	v_lshl_add_u64 v[18:19], v[0:1], 0, s[2:3]
	v_lshl_add_u64 v[0:1], s[0:1], 0, v[184:185]
	v_ashrrev_i32_e32 v13, 31, v12
	v_lshl_add_u64 v[16:17], v[0:1], 0, s[94:95]
	v_lshl_add_u64 v[0:1], v[12:13], 4, v[18:19]
	v_lshl_add_u64 v[4:5], v[12:13], 0, s[96:97]
	global_load_dword v2, v[0:1], off
	v_lshl_add_u64 v[0:1], v[4:5], 4, v[18:19]
	v_lshl_add_u64 v[6:7], v[12:13], 0, s[4:5]
	global_load_dword v3, v[0:1], off
	v_lshl_add_u64 v[0:1], v[6:7], 4, v[18:19]
	global_load_dword v0, v[0:1], off
	v_mov_b64_e32 v[20:21], s[0:1]
	v_lshlrev_b64 v[4:5], 9, v[4:5]
	v_mad_i64_i32 v[22:23], s[0:1], v12, s33, v[20:21]
	v_lshl_add_u64 v[4:5], v[16:17], 0, v[4:5]
	v_lshl_add_u64 v[26:27], v[22:23], 0, v[184:185]
	s_add_i32 s6, s6, 1
	v_mov_b32_e32 v168, s93
	v_mov_b32_e32 v169, 0
	v_mov_b32_e32 v161, 0
	v_add_u32_e32 v160, 0x100, v31
	v_ashrrev_i32_e32 v160, 5, v160
	v_lshl_add_u64 v[162:163], v[160:161], 0, s[96:97]
	v_lshl_add_u64 v[164:165], v[160:161], 0, s[4:5]
	v_lshl_add_u64 v[166:167], v[160:161], 4, v[18:19]
	global_load_dword v150, v[166:167], off
	v_lshl_add_u64 v[166:167], v[162:163], 4, v[18:19]
	global_load_dword v151, v[166:167], off
	v_lshl_add_u64 v[166:167], v[164:165], 4, v[18:19]
	global_load_dword v152, v[166:167], off
	v_lshl_add_u64 v[162:163], v[160:161], 0, s[96:97]
	v_lshl_add_u64 v[164:165], v[160:161], 0, s[4:5]
	v_lshlrev_b64 v[166:167], 9, v[160:161]
	v_lshl_add_u64 v[166:167], v[16:17], 0, v[166:167]
	global_load_dwordx4 v[56:59], v[166:167], off nt
	v_lshlrev_b64 v[166:167], 9, v[162:163]
	v_lshl_add_u64 v[166:167], v[16:17], 0, v[166:167]
	global_load_dwordx4 v[60:63], v[166:167], off nt
	v_lshlrev_b64 v[166:167], 9, v[164:165]
	v_lshl_add_u64 v[166:167], v[16:17], 0, v[166:167]
	global_load_dwordx4 v[100:103], v[166:167], off nt
	v_mad_i64_i32 v[166:167], s[0:1], v160, s33, v[20:21]
	v_lshl_add_u64 v[166:167], v[166:167], 0, v[184:185]
	v_lshl_add_u64 v[166:167], v[166:167], 0, v[168:169]
	global_load_dwordx4 v[104:107], v[166:167], off offset:3328 nt
	v_add_u32_e32 v160, 0x200, v31
	v_ashrrev_i32_e32 v160, 5, v160
	v_lshl_add_u64 v[162:163], v[160:161], 0, s[96:97]
	v_lshl_add_u64 v[164:165], v[160:161], 0, s[4:5]
	v_lshl_add_u64 v[166:167], v[160:161], 4, v[18:19]
	global_load_dword v153, v[166:167], off
	v_lshl_add_u64 v[166:167], v[162:163], 4, v[18:19]
	global_load_dword v154, v[166:167], off
	v_lshl_add_u64 v[166:167], v[164:165], 4, v[18:19]
	global_load_dword v155, v[166:167], off
	v_lshl_add_u64 v[162:163], v[160:161], 0, s[96:97]
	v_lshl_add_u64 v[164:165], v[160:161], 0, s[4:5]
	v_lshlrev_b64 v[166:167], 9, v[160:161]
	v_lshl_add_u64 v[166:167], v[16:17], 0, v[166:167]
	global_load_dwordx4 v[108:111], v[166:167], off nt
	v_lshlrev_b64 v[166:167], 9, v[162:163]
	v_lshl_add_u64 v[166:167], v[16:17], 0, v[166:167]
	global_load_dwordx4 v[112:115], v[166:167], off nt
	v_lshlrev_b64 v[166:167], 9, v[164:165]
	v_lshl_add_u64 v[166:167], v[16:17], 0, v[166:167]
	global_load_dwordx4 v[120:123], v[166:167], off nt
	v_mad_i64_i32 v[166:167], s[0:1], v160, s33, v[20:21]
	v_lshl_add_u64 v[166:167], v[166:167], 0, v[184:185]
	v_lshl_add_u64 v[166:167], v[166:167], 0, v[168:169]
	global_load_dwordx4 v[124:127], v[166:167], off offset:3328 nt
	v_add_u32_e32 v160, 0x300, v31
	v_ashrrev_i32_e32 v160, 5, v160
	v_lshl_add_u64 v[162:163], v[160:161], 0, s[96:97]
	v_lshl_add_u64 v[164:165], v[160:161], 0, s[4:5]
	v_lshl_add_u64 v[166:167], v[160:161], 4, v[18:19]
	global_load_dword v156, v[166:167], off
	v_lshl_add_u64 v[166:167], v[162:163], 4, v[18:19]
	global_load_dword v157, v[166:167], off
	v_lshl_add_u64 v[166:167], v[164:165], 4, v[18:19]
	global_load_dword v158, v[166:167], off
	v_lshl_add_u64 v[162:163], v[160:161], 0, s[96:97]
	v_lshl_add_u64 v[164:165], v[160:161], 0, s[4:5]
	v_lshlrev_b64 v[166:167], 9, v[160:161]
	v_lshl_add_u64 v[166:167], v[16:17], 0, v[166:167]
	global_load_dwordx4 v[128:131], v[166:167], off nt
	v_lshlrev_b64 v[166:167], 9, v[162:163]
	v_lshl_add_u64 v[166:167], v[16:17], 0, v[166:167]
	global_load_dwordx4 v[132:135], v[166:167], off nt
	v_lshlrev_b64 v[166:167], 9, v[164:165]
	v_lshl_add_u64 v[166:167], v[16:17], 0, v[166:167]
	global_load_dwordx4 v[136:139], v[166:167], off nt
	v_mad_i64_i32 v[166:167], s[0:1], v160, s33, v[20:21]
	v_lshl_add_u64 v[166:167], v[166:167], 0, v[184:185]
	v_lshl_add_u64 v[166:167], v[166:167], 0, v[168:169]
	global_load_dwordx4 v[140:143], v[166:167], off offset:3328 nt
	v_lshl_add_u64 v[162:163], v[12:13], 0, s[96:97]
	v_lshl_add_u64 v[164:165], v[12:13], 0, s[4:5]
	v_lshlrev_b64 v[166:167], 9, v[12:13]
	v_lshl_add_u64 v[166:167], v[16:17], 0, v[166:167]
	global_load_dwordx4 v[40:43], v[166:167], off nt
	v_lshlrev_b64 v[166:167], 9, v[162:163]
	v_lshl_add_u64 v[166:167], v[16:17], 0, v[166:167]
	global_load_dwordx4 v[44:47], v[166:167], off nt
	v_lshlrev_b64 v[166:167], 9, v[164:165]
	v_lshl_add_u64 v[166:167], v[16:17], 0, v[166:167]
	global_load_dwordx4 v[48:51], v[166:167], off nt
	v_mad_i64_i32 v[166:167], s[0:1], v12, s33, v[20:21]
	v_lshl_add_u64 v[166:167], v[166:167], 0, v[184:185]
	v_lshl_add_u64 v[166:167], v[166:167], 0, v[168:169]
	global_load_dwordx4 v[52:55], v[166:167], off offset:3328 nt
	s_waitcnt vmcnt(0)
; DI float lo16(unsigned w) { return __uint_as_float(w << 16); }
; DI float hi16(unsigned w) { return __uint_as_float(w & 0xffff0000u); }
; DI float siluf_(float x) { return x / (1.f + __expf(-x)); }
; DI void dilcomb_item(const Params& p, int it) {
;     ...
;     const float l0 = lse[((size_t)0 * T_ + tok) * 4 + h], l1 = lse[((size_t)1 * T_ + tok) * 4 + h], l2 = lse[((size_t)2 * T_ + tok) * 4 + h];
;     const float mx = fmaxf(l0, fmaxf(l1, l2));
;     float w0 = __expf(l0 - mx), w1 = __expf(l1 - mx), w2 = __expf(l2 - mx);
;     const float iw = 1.f / (w0 + w1 + w2); w0 *= iw; w1 *= iw; w2 *= iw;
;     const u32x4 a = *(const u32x4*)(od + ((size_t)0 * T_ + tok) * 256 + c8 * 8), bq = *(const u32x4*)(od + ((size_t)1 * T_ + tok) * 256 + c8 * 8), cq = *(const u32x4*)(od + ((size_t)2 * T_ + tok) * 256 + c8 * 8);
;     const u32x4 z = *(const u32x4*)(proj + tok * NP + C_BZ + c8 * 8);
;     u32x4 r;
; #pragma unroll
;     for (int e = 0; e < 4; ++e) {
;       const float v0 = (w0 * lo16(a[e]) + w1 * lo16(bq[e]) + w2 * lo16(cq[e])) * siluf_(lo16(z[e]));
;       const float v1 = (w0 * hi16(a[e]) + w1 * hi16(bq[e]) + w2 * hi16(cq[e])) * siluf_(hi16(z[e]));
;       r[e] = pk2(v0, v1);
;     }
;     *(u32x4*)(y + tok * 1024 + 256 + c8 * 8) = r;
	v_max3_f32 v1, v2, v3, v0
	v_sub_f32_e32 v2, v2, v1
	v_mul_f32_e32 v2, 0x3fb8aa3b, v2
	v_exp_f32_e32 v25, v2
	v_sub_f32_e32 v2, v3, v1
	v_mul_f32_e32 v2, 0x3fb8aa3b, v2
	v_sub_f32_e32 v0, v0, v1
	v_exp_f32_e32 v24, v2
	v_mul_f32_e32 v0, 0x3fb8aa3b, v0
	v_exp_f32_e32 v0, v0
	v_add_f32_e32 v1, v25, v24
	v_add_f32_e32 v1, v0, v1
	s_nop 0
	v_rcp_f32_e32 v30, v1
	s_nop 0
	v_mul_f32_e32 v14, v0, v30
	v_lshlrev_b64 v[0:1], 9, v[12:13]
	v_lshl_add_u64 v[0:1], v[16:17], 0, v[0:1]
	v_mov_b32_e32 v0, v40
	v_mov_b32_e32 v1, v41
	v_mov_b32_e32 v2, v42
	v_mov_b32_e32 v3, v43
	v_add_co_u32_e32 v26, vcc, s93, v26
	v_mov_b32_e32 v8, v44
	v_mov_b32_e32 v9, v45
	v_mov_b32_e32 v10, v46
	v_mov_b32_e32 v11, v47
	v_lshlrev_b64 v[4:5], 9, v[6:7]
	v_lshl_add_u64 v[4:5], v[16:17], 0, v[4:5]
	v_addc_co_u32_e32 v27, vcc, 0, v27, vcc
	v_mov_b32_e32 v4, v48
	v_mov_b32_e32 v5, v49
	v_mov_b32_e32 v6, v50
	v_mov_b32_e32 v7, v51
	v_pk_mul_f32 v[24:25], v[24:25], v[30:31] op_sel_hi:[1,0]
	v_mov_b32_e32 v26, v52
	v_mov_b32_e32 v27, v53
	v_mov_b32_e32 v28, v54
	v_mov_b32_e32 v29, v55
	v_and_b32_e32 v35, 0xffff0000, v0
	v_lshlrev_b32_e32 v36, 16, v0
	v_lshlrev_b32_e32 v34, 16, v8
	v_and_b32_e32 v37, 0xffff0000, v8
	v_pk_mul_f32 v[36:37], v[24:25], v[36:37] op_sel:[1,0] op_sel_hi:[0,1]
	v_pk_fma_f32 v[34:35], v[24:25], v[34:35], v[36:37]
	v_lshlrev_b32_e32 v38, 16, v4
	v_and_b32_e32 v39, 0xffff0000, v4
	v_lshlrev_b32_e32 v13, 16, v26
	v_and_b32_e32 v15, 0xffff0000, v26
	v_mul_f32_e32 v26, 0xbfb8aa3b, v13
	v_mul_f32_e32 v0, 0xbfb8aa3b, v15
	v_exp_f32_e32 v32, v26
	v_exp_f32_e32 v33, v0
	s_nop 0
	v_pk_add_f32 v[32:33], v[32:33], 1.0 op_sel_hi:[1,0]
	s_nop 0
	s_nop 0
	v_rcp_f32_e32 v33, v33
	s_nop 0
	v_mul_f32_e32 v33, v15, v33
	v_div_scale_f32 v0, s[0:1], v32, v32, v13
	v_rcp_f32_e32 v4, v0
	s_nop 0
	v_fma_f32 v8, -v0, v4, 1.0
	v_fmac_f32_e32 v4, v8, v4
	v_div_scale_f32 v8, vcc, v13, v32, v13
	v_mul_f32_e32 v15, v8, v4
	v_fma_f32 v26, -v0, v15, v8
	v_fmac_f32_e32 v15, v26, v4
	v_fma_f32 v0, -v0, v15, v8
	v_div_fmas_f32 v0, v0, v4, v15
	v_div_fixup_f32 v32, v0, v32, v13
	v_pk_fma_f32 v[34:35], v[14:15], v[38:39], v[34:35] op_sel_hi:[0,1,1]
	v_lshlrev_b32_e32 v13, 16, v27
	v_and_b32_e32 v15, 0xffff0000, v27
	v_pk_mul_f32 v[32:33], v[32:33], v[34:35]
	v_mul_f32_e32 v4, 0xbfb8aa3b, v13
	v_and_b32_e32 v27, 0xffff0000, v1
	v_lshlrev_b32_e32 v8, 16, v1
	v_mul_f32_e32 v1, 0xbfb8aa3b, v15
	v_cvt_pk_bf16_f32 v0, v32, v33
	v_exp_f32_e32 v4, v4
	v_lshlrev_b32_e32 v32, 16, v5
	v_and_b32_e32 v33, 0xffff0000, v5
	v_exp_f32_e32 v5, v1
	v_lshlrev_b32_e32 v26, 16, v9
	v_and_b32_e32 v9, 0xffff0000, v9
	v_pk_mul_f32 v[8:9], v[24:25], v[8:9] op_sel:[1,0] op_sel_hi:[0,1]
	v_pk_add_f32 v[4:5], v[4:5], 1.0 op_sel_hi:[1,0]
	v_pk_fma_f32 v[8:9], v[24:25], v[26:27], v[8:9]
	v_lshlrev_b32_e32 v26, 16, v2
	v_and_b32_e32 v27, 0xffff0000, v10
	v_pk_mul_f32 v[26:27], v[24:25], v[26:27] op_sel:[1,0] op_sel_hi:[0,1]
	v_rcp_f32_e32 v5, v5
	s_nop 0
	v_mul_f32_e32 v5, v15, v5
	v_div_scale_f32 v1, s[0:1], v4, v4, v13
	v_rcp_f32_e32 v15, v1
	s_nop 0
	v_fma_f32 v30, -v1, v15, 1.0
	v_fmac_f32_e32 v15, v30, v15
	v_div_scale_f32 v30, vcc, v13, v4, v13
	v_mul_f32_e32 v34, v30, v15
	v_fma_f32 v35, -v1, v34, v30
	v_fmac_f32_e32 v34, v35, v15
	v_fma_f32 v1, -v1, v34, v30
	v_div_fmas_f32 v1, v1, v15, v34
	v_div_fixup_f32 v4, v1, v4, v13
	v_pk_fma_f32 v[8:9], v[14:15], v[32:33], v[8:9] op_sel_hi:[0,1,1]
	v_pk_mul_f32 v[4:5], v[4:5], v[8:9]
	v_lshlrev_b32_e32 v13, 16, v28
	v_and_b32_e32 v15, 0xffff0000, v28
	v_cvt_pk_bf16_f32 v1, v4, v5
	v_mul_f32_e32 v4, 0xbfb8aa3b, v13
	v_and_b32_e32 v9, 0xffff0000, v2
	v_mul_f32_e32 v2, 0xbfb8aa3b, v15
	v_exp_f32_e32 v4, v4
	v_exp_f32_e32 v5, v2
	v_lshlrev_b32_e32 v32, 16, v6
	v_and_b32_e32 v33, 0xffff0000, v6
	v_lshlrev_b32_e32 v8, 16, v10
	v_pk_add_f32 v[4:5], v[4:5], 1.0 op_sel_hi:[1,0]
	v_pk_fma_f32 v[8:9], v[24:25], v[8:9], v[26:27]
	s_nop 0
	v_rcp_f32_e32 v5, v5
	s_nop 0
	v_mul_f32_e32 v5, v15, v5
	v_div_scale_f32 v2, s[0:1], v4, v4, v13
	v_rcp_f32_e32 v6, v2
	s_nop 0
	v_fma_f32 v10, -v2, v6, 1.0
	v_fmac_f32_e32 v6, v10, v6
	v_div_scale_f32 v10, vcc, v13, v4, v13
	v_mul_f32_e32 v15, v10, v6
	v_fma_f32 v28, -v2, v15, v10
	v_fmac_f32_e32 v15, v28, v6
	v_fma_f32 v2, -v2, v15, v10
	v_div_fmas_f32 v2, v2, v6, v15
	v_div_fixup_f32 v4, v2, v4, v13
	v_pk_fma_f32 v[8:9], v[14:15], v[32:33], v[8:9] op_sel_hi:[0,1,1]
	v_pk_mul_f32 v[4:5], v[4:5], v[8:9]
	v_lshlrev_b32_e32 v13, 16, v29
	v_and_b32_e32 v15, 0xffff0000, v29
	v_cvt_pk_bf16_f32 v2, v4, v5
	v_mul_f32_e32 v4, 0xbfb8aa3b, v13
	v_and_b32_e32 v9, 0xffff0000, v3
	v_lshlrev_b32_e32 v10, 16, v3
	v_mul_f32_e32 v3, 0xbfb8aa3b, v15
	v_exp_f32_e32 v4, v4
	v_exp_f32_e32 v5, v3
	v_lshlrev_b32_e32 v8, 16, v11
	v_and_b32_e32 v11, 0xffff0000, v11
	v_pk_mul_f32 v[10:11], v[24:25], v[10:11] op_sel:[1,0] op_sel_hi:[0,1]
	v_pk_add_f32 v[4:5], v[4:5], 1.0 op_sel_hi:[1,0]
	v_pk_fma_f32 v[8:9], v[24:25], v[8:9], v[10:11]
	v_lshlrev_b32_e32 v6, 16, v7
	v_and_b32_e32 v7, 0xffff0000, v7
	v_pk_fma_f32 v[6:7], v[14:15], v[6:7], v[8:9] op_sel_hi:[0,1,1]
	s_nop 0
	v_rcp_f32_e32 v5, v5
	s_nop 0
	v_mul_f32_e32 v5, v15, v5
	s_nop 0
	v_rcp_f32_e32 v4, v4
	s_nop 0
	v_mul_f32_e32 v4, v13, v4
	v_pk_mul_f32 v[4:5], v[4:5], v[6:7]
	s_nop 0
	v_cvt_pk_bf16_f32 v3, v4, v5
	v_mad_i64_i32 v[4:5], s[0:1], v12, s37, v[22:23]
	v_lshl_add_u64 v[4:5], v[4:5], 0, v[184:185]
	v_add_co_u32_e32 v4, vcc, s74, v4
	s_nop 1
	v_addc_co_u32_e32 v5, vcc, 0, v5, vcc
	global_store_dwordx4 v[4:5], v[0:3], off offset:512
	s_nop 1
	v_add_u32_e32 v0, 0x100, v31
	v_ashrrev_i32_e32 v22, 5, v0
	v_ashrrev_i32_e32 v23, 31, v22
	v_lshl_add_u64 v[0:1], v[22:23], 4, v[18:19]
	v_lshl_add_u64 v[4:5], v[22:23], 0, s[96:97]
; DI float lo16(unsigned w) { return __uint_as_float(w << 16); }
; DI float hi16(unsigned w) { return __uint_as_float(w & 0xffff0000u); }
; DI float siluf_(float x) { return x / (1.f + __expf(-x)); }
; DI void dilcomb_item(const Params& p, int it) {
;     ...
;     const float l0 = lse[((size_t)0 * T_ + tok) * 4 + h], l1 = lse[((size_t)1 * T_ + tok) * 4 + h], l2 = lse[((size_t)2 * T_ + tok) * 4 + h];
;     const float mx = fmaxf(l0, fmaxf(l1, l2));
;     float w0 = __expf(l0 - mx), w1 = __expf(l1 - mx), w2 = __expf(l2 - mx);
;     const float iw = 1.f / (w0 + w1 + w2); w0 *= iw; w1 *= iw; w2 *= iw;
;     const u32x4 a = *(const u32x4*)(od + ((size_t)0 * T_ + tok) * 256 + c8 * 8), bq = *(const u32x4*)(od + ((size_t)1 * T_ + tok) * 256 + c8 * 8), cq = *(const u32x4*)(od + ((size_t)2 * T_ + tok) * 256 + c8 * 8);
;     const u32x4 z = *(const u32x4*)(proj + tok * NP + C_BZ + c8 * 8);
;     u32x4 r;
; #pragma unroll
;     for (int e = 0; e < 4; ++e) {
;       const float v0 = (w0 * lo16(a[e]) + w1 * lo16(bq[e]) + w2 * lo16(cq[e])) * siluf_(lo16(z[e]));
;       const float v1 = (w0 * hi16(a[e]) + w1 * hi16(bq[e]) + w2 * hi16(cq[e])) * siluf_(hi16(z[e]));
;       r[e] = pk2(v0, v1);
;     }
;     *(u32x4*)(y + tok * 1024 + 256 + c8 * 8) = r;
	v_mov_b32_e32 v2, v150
	v_lshl_add_u64 v[0:1], v[4:5], 4, v[18:19]
	v_lshl_add_u64 v[6:7], v[22:23], 0, s[4:5]
	v_mov_b32_e32 v3, v151
	v_lshl_add_u64 v[0:1], v[6:7], 4, v[18:19]
	v_mov_b32_e32 v0, v152
	v_lshlrev_b64 v[4:5], 9, v[4:5]
	v_mad_i64_i32 v[26:27], s[0:1], v22, s33, v[20:21]
	v_lshl_add_u64 v[4:5], v[16:17], 0, v[4:5]
	v_lshl_add_u64 v[12:13], v[26:27], 0, v[184:185]
	v_max3_f32 v1, v2, v3, v0
	v_sub_f32_e32 v2, v2, v1
	v_mul_f32_e32 v2, 0x3fb8aa3b, v2
	v_exp_f32_e32 v29, v2
	v_sub_f32_e32 v2, v3, v1
	v_mul_f32_e32 v2, 0x3fb8aa3b, v2
	v_sub_f32_e32 v0, v0, v1
	v_exp_f32_e32 v28, v2
	v_mul_f32_e32 v0, 0x3fb8aa3b, v0
	v_exp_f32_e32 v0, v0
	v_add_f32_e32 v1, v29, v28
	v_add_f32_e32 v1, v0, v1
	s_nop 0
	v_rcp_f32_e32 v30, v1
	s_nop 0
	v_mul_f32_e32 v24, v0, v30
	v_lshlrev_b64 v[0:1], 9, v[22:23]
	v_lshl_add_u64 v[0:1], v[16:17], 0, v[0:1]
	v_mov_b32_e32 v0, v56
	v_mov_b32_e32 v1, v57
	v_mov_b32_e32 v2, v58
	v_mov_b32_e32 v3, v59
	v_add_co_u32_e32 v12, vcc, s93, v12
	v_mov_b32_e32 v8, v60
	v_mov_b32_e32 v9, v61
	v_mov_b32_e32 v10, v62
	v_mov_b32_e32 v11, v63
	v_lshlrev_b64 v[4:5], 9, v[6:7]
	v_lshl_add_u64 v[4:5], v[16:17], 0, v[4:5]
	v_addc_co_u32_e32 v13, vcc, 0, v13, vcc
	v_mov_b32_e32 v4, v100
	v_mov_b32_e32 v5, v101
	v_mov_b32_e32 v6, v102
	v_mov_b32_e32 v7, v103
	v_pk_mul_f32 v[28:29], v[28:29], v[30:31] op_sel_hi:[1,0]
	v_mov_b32_e32 v12, v104
	v_mov_b32_e32 v13, v105
	v_mov_b32_e32 v14, v106
	v_mov_b32_e32 v15, v107
	v_and_b32_e32 v35, 0xffff0000, v0
	v_lshlrev_b32_e32 v36, 16, v0
	v_lshlrev_b32_e32 v34, 16, v8
	v_and_b32_e32 v37, 0xffff0000, v8
	v_pk_mul_f32 v[36:37], v[28:29], v[36:37] op_sel:[1,0] op_sel_hi:[0,1]
	v_pk_fma_f32 v[34:35], v[28:29], v[34:35], v[36:37]
	v_lshlrev_b32_e32 v38, 16, v4
	v_and_b32_e32 v39, 0xffff0000, v4
	v_lshlrev_b32_e32 v23, 16, v12
	v_and_b32_e32 v12, 0xffff0000, v12
	v_mul_f32_e32 v25, 0xbfb8aa3b, v23
	v_mul_f32_e32 v0, 0xbfb8aa3b, v12
	v_exp_f32_e32 v32, v25
	v_exp_f32_e32 v33, v0
	s_nop 0
	v_pk_add_f32 v[32:33], v[32:33], 1.0 op_sel_hi:[1,0]
	s_nop 0
	s_nop 0
	v_rcp_f32_e32 v33, v33
	s_nop 0
	v_mul_f32_e32 v33, v12, v33
	v_div_scale_f32 v0, s[0:1], v32, v32, v23
	v_rcp_f32_e32 v4, v0
	s_nop 0
	v_fma_f32 v8, -v0, v4, 1.0
	v_fmac_f32_e32 v4, v8, v4
	v_div_scale_f32 v8, vcc, v23, v32, v23
	v_mul_f32_e32 v12, v8, v4
	v_fma_f32 v25, -v0, v12, v8
	v_fmac_f32_e32 v12, v25, v4
	v_fma_f32 v0, -v0, v12, v8
	v_div_fmas_f32 v0, v0, v4, v12
	v_div_fixup_f32 v32, v0, v32, v23
	v_pk_fma_f32 v[34:35], v[24:25], v[38:39], v[34:35] op_sel_hi:[0,1,1]
	v_lshlrev_b32_e32 v23, 16, v13
	v_and_b32_e32 v25, 0xffff0000, v13
	v_pk_mul_f32 v[32:33], v[32:33], v[34:35]
	v_mul_f32_e32 v4, 0xbfb8aa3b, v23
	v_and_b32_e32 v13, 0xffff0000, v1
	v_lshlrev_b32_e32 v8, 16, v1
	v_mul_f32_e32 v1, 0xbfb8aa3b, v25
	v_cvt_pk_bf16_f32 v0, v32, v33
	v_exp_f32_e32 v4, v4
	v_lshlrev_b32_e32 v32, 16, v5
	v_and_b32_e32 v33, 0xffff0000, v5
	v_exp_f32_e32 v5, v1
	v_lshlrev_b32_e32 v12, 16, v9
	v_and_b32_e32 v9, 0xffff0000, v9
	v_pk_mul_f32 v[8:9], v[28:29], v[8:9] op_sel:[1,0] op_sel_hi:[0,1]
	v_pk_add_f32 v[4:5], v[4:5], 1.0 op_sel_hi:[1,0]
	v_pk_fma_f32 v[8:9], v[28:29], v[12:13], v[8:9]
	v_lshlrev_b32_e32 v12, 16, v2
	v_and_b32_e32 v13, 0xffff0000, v10
	v_pk_mul_f32 v[12:13], v[28:29], v[12:13] op_sel:[1,0] op_sel_hi:[0,1]
	v_rcp_f32_e32 v5, v5
	s_nop 0
	v_mul_f32_e32 v5, v25, v5
	v_div_scale_f32 v1, s[0:1], v4, v4, v23
	v_rcp_f32_e32 v25, v1
	s_nop 0
	v_fma_f32 v30, -v1, v25, 1.0
	v_fmac_f32_e32 v25, v30, v25
	v_div_scale_f32 v30, vcc, v23, v4, v23
	v_mul_f32_e32 v34, v30, v25
	v_fma_f32 v35, -v1, v34, v30
	v_fmac_f32_e32 v34, v35, v25
	v_fma_f32 v1, -v1, v34, v30
	v_div_fmas_f32 v1, v1, v25, v34
	v_div_fixup_f32 v4, v1, v4, v23
	v_pk_fma_f32 v[8:9], v[24:25], v[32:33], v[8:9] op_sel_hi:[0,1,1]
	v_pk_mul_f32 v[4:5], v[4:5], v[8:9]
	v_lshlrev_b32_e32 v23, 16, v14
	v_and_b32_e32 v14, 0xffff0000, v14
	v_cvt_pk_bf16_f32 v1, v4, v5
	v_mul_f32_e32 v4, 0xbfb8aa3b, v23
	v_and_b32_e32 v9, 0xffff0000, v2
	v_mul_f32_e32 v2, 0xbfb8aa3b, v14
	v_exp_f32_e32 v4, v4
	v_exp_f32_e32 v5, v2
	v_lshlrev_b32_e32 v32, 16, v6
	v_and_b32_e32 v33, 0xffff0000, v6
	v_lshlrev_b32_e32 v8, 16, v10
	v_pk_add_f32 v[4:5], v[4:5], 1.0 op_sel_hi:[1,0]
	v_pk_fma_f32 v[8:9], v[28:29], v[8:9], v[12:13]
	v_lshlrev_b32_e32 v12, 16, v15
	v_and_b32_e32 v13, 0xffff0000, v15
	v_rcp_f32_e32 v5, v5
	s_nop 0
	v_mul_f32_e32 v5, v14, v5
	v_div_scale_f32 v2, s[0:1], v4, v4, v23
	v_rcp_f32_e32 v6, v2
	s_nop 0
	v_fma_f32 v10, -v2, v6, 1.0
	v_fmac_f32_e32 v6, v10, v6
	v_div_scale_f32 v10, vcc, v23, v4, v23
	v_mul_f32_e32 v14, v10, v6
	v_fma_f32 v25, -v2, v14, v10
	v_fmac_f32_e32 v14, v25, v6
	v_fma_f32 v2, -v2, v14, v10
	v_div_fmas_f32 v2, v2, v6, v14
	v_div_fixup_f32 v4, v2, v4, v23
	v_pk_fma_f32 v[8:9], v[24:25], v[32:33], v[8:9] op_sel_hi:[0,1,1]
	v_pk_mul_f32 v[4:5], v[4:5], v[8:9]
	v_and_b32_e32 v9, 0xffff0000, v3
	v_cvt_pk_bf16_f32 v2, v4, v5
	v_mul_f32_e32 v4, 0xbfb8aa3b, v12
	v_lshlrev_b32_e32 v10, 16, v3
	v_mul_f32_e32 v3, 0xbfb8aa3b, v13
	v_exp_f32_e32 v4, v4
	v_exp_f32_e32 v5, v3
	v_lshlrev_b32_e32 v8, 16, v11
	v_and_b32_e32 v11, 0xffff0000, v11
	v_pk_mul_f32 v[10:11], v[28:29], v[10:11] op_sel:[1,0] op_sel_hi:[0,1]
	v_pk_add_f32 v[4:5], v[4:5], 1.0 op_sel_hi:[1,0]
	v_pk_fma_f32 v[8:9], v[28:29], v[8:9], v[10:11]
	v_lshlrev_b32_e32 v6, 16, v7
	v_and_b32_e32 v7, 0xffff0000, v7
	v_pk_fma_f32 v[6:7], v[24:25], v[6:7], v[8:9] op_sel_hi:[0,1,1]
	s_nop 0
	v_rcp_f32_e32 v5, v5
	s_nop 0
	v_mul_f32_e32 v5, v13, v5
	s_nop 0
	v_rcp_f32_e32 v4, v4
	s_nop 0
	v_mul_f32_e32 v4, v12, v4
	v_pk_mul_f32 v[4:5], v[4:5], v[6:7]
	s_nop 0
	v_cvt_pk_bf16_f32 v3, v4, v5
	v_mad_i64_i32 v[4:5], s[0:1], v22, s37, v[26:27]
; DI float lo16(unsigned w) { return __uint_as_float(w << 16); }
; DI float hi16(unsigned w) { return __uint_as_float(w & 0xffff0000u); }
; DI float siluf_(float x) { return x / (1.f + __expf(-x)); }
; DI void dilcomb_item(const Params& p, int it) {
;     ...
;     const float l0 = lse[((size_t)0 * T_ + tok) * 4 + h], l1 = lse[((size_t)1 * T_ + tok) * 4 + h], l2 = lse[((size_t)2 * T_ + tok) * 4 + h];
;     const float mx = fmaxf(l0, fmaxf(l1, l2));
;     float w0 = __expf(l0 - mx), w1 = __expf(l1 - mx), w2 = __expf(l2 - mx);
;     const float iw = 1.f / (w0 + w1 + w2); w0 *= iw; w1 *= iw; w2 *= iw;
;     const u32x4 a = *(const u32x4*)(od + ((size_t)0 * T_ + tok) * 256 + c8 * 8), bq = *(const u32x4*)(od + ((size_t)1 * T_ + tok) * 256 + c8 * 8), cq = *(const u32x4*)(od + ((size_t)2 * T_ + tok) * 256 + c8 * 8);
;     const u32x4 z = *(const u32x4*)(proj + tok * NP + C_BZ + c8 * 8);
;     u32x4 r;
; #pragma unroll
;     for (int e = 0; e < 4; ++e) {
;       const float v0 = (w0 * lo16(a[e]) + w1 * lo16(bq[e]) + w2 * lo16(cq[e])) * siluf_(lo16(z[e]));
;       const float v1 = (w0 * hi16(a[e]) + w1 * hi16(bq[e]) + w2 * hi16(cq[e])) * siluf_(hi16(z[e]));
;       r[e] = pk2(v0, v1);
;     }
;     *(u32x4*)(y + tok * 1024 + 256 + c8 * 8) = r;
	v_lshl_add_u64 v[4:5], v[4:5], 0, v[184:185]
	v_add_co_u32_e32 v4, vcc, s74, v4
	s_nop 1
	v_addc_co_u32_e32 v5, vcc, 0, v5, vcc
	global_store_dwordx4 v[4:5], v[0:3], off offset:512
	s_nop 1
	v_add_u32_e32 v0, 0x200, v31
	v_ashrrev_i32_e32 v12, 5, v0
	v_ashrrev_i32_e32 v13, 31, v12
	v_lshl_add_u64 v[0:1], v[12:13], 4, v[18:19]
	v_lshl_add_u64 v[4:5], v[12:13], 0, s[96:97]
	v_mov_b32_e32 v2, v153
	v_lshl_add_u64 v[0:1], v[4:5], 4, v[18:19]
	v_lshl_add_u64 v[6:7], v[12:13], 0, s[4:5]
	v_mov_b32_e32 v3, v154
	v_lshl_add_u64 v[0:1], v[6:7], 4, v[18:19]
	v_mov_b32_e32 v0, v155
	v_lshlrev_b64 v[4:5], 9, v[4:5]
	v_mad_i64_i32 v[22:23], s[0:1], v12, s33, v[20:21]
	v_lshl_add_u64 v[4:5], v[16:17], 0, v[4:5]
	v_lshl_add_u64 v[24:25], v[22:23], 0, v[184:185]
	v_max3_f32 v1, v2, v3, v0
	v_sub_f32_e32 v2, v2, v1
	v_mul_f32_e32 v2, 0x3fb8aa3b, v2
	v_exp_f32_e32 v29, v2
	v_sub_f32_e32 v2, v3, v1
	v_mul_f32_e32 v2, 0x3fb8aa3b, v2
	v_sub_f32_e32 v0, v0, v1
	v_exp_f32_e32 v28, v2
	v_mul_f32_e32 v0, 0x3fb8aa3b, v0
	v_exp_f32_e32 v0, v0
	v_add_f32_e32 v1, v29, v28
	v_add_f32_e32 v1, v0, v1
	s_nop 0
	v_rcp_f32_e32 v30, v1
	s_nop 0
	v_mul_f32_e32 v14, v0, v30
	v_lshlrev_b64 v[0:1], 9, v[12:13]
	v_lshl_add_u64 v[0:1], v[16:17], 0, v[0:1]
	v_mov_b32_e32 v0, v108
	v_mov_b32_e32 v1, v109
	v_mov_b32_e32 v2, v110
	v_mov_b32_e32 v3, v111
	v_add_co_u32_e32 v24, vcc, s93, v24
	v_mov_b32_e32 v8, v112
	v_mov_b32_e32 v9, v113
	v_mov_b32_e32 v10, v114
	v_mov_b32_e32 v11, v115
	v_lshlrev_b64 v[4:5], 9, v[6:7]
	v_lshl_add_u64 v[4:5], v[16:17], 0, v[4:5]
	v_addc_co_u32_e32 v25, vcc, 0, v25, vcc
	v_mov_b32_e32 v4, v120
	v_mov_b32_e32 v5, v121
	v_mov_b32_e32 v6, v122
	v_mov_b32_e32 v7, v123
	v_pk_mul_f32 v[28:29], v[28:29], v[30:31] op_sel_hi:[1,0]
	v_mov_b32_e32 v24, v124
	v_mov_b32_e32 v25, v125
	v_mov_b32_e32 v26, v126
	v_mov_b32_e32 v27, v127
	v_and_b32_e32 v35, 0xffff0000, v0
	v_lshlrev_b32_e32 v36, 16, v0
	v_lshlrev_b32_e32 v34, 16, v8
	v_and_b32_e32 v37, 0xffff0000, v8
	v_pk_mul_f32 v[36:37], v[28:29], v[36:37] op_sel:[1,0] op_sel_hi:[0,1]
	v_pk_fma_f32 v[34:35], v[28:29], v[34:35], v[36:37]
	v_lshlrev_b32_e32 v38, 16, v4
	v_and_b32_e32 v39, 0xffff0000, v4
	v_lshlrev_b32_e32 v13, 16, v24
	v_and_b32_e32 v15, 0xffff0000, v24
	v_mul_f32_e32 v24, 0xbfb8aa3b, v13
	v_mul_f32_e32 v0, 0xbfb8aa3b, v15
	v_exp_f32_e32 v32, v24
	v_exp_f32_e32 v33, v0
	s_nop 0
	v_pk_add_f32 v[32:33], v[32:33], 1.0 op_sel_hi:[1,0]
	s_nop 0
	s_nop 0
	v_rcp_f32_e32 v33, v33
	s_nop 0
	v_mul_f32_e32 v33, v15, v33
	v_div_scale_f32 v0, s[0:1], v32, v32, v13
	v_rcp_f32_e32 v4, v0
	s_nop 0
	v_fma_f32 v8, -v0, v4, 1.0
	v_fmac_f32_e32 v4, v8, v4
	v_div_scale_f32 v8, vcc, v13, v32, v13
	v_mul_f32_e32 v15, v8, v4
	v_fma_f32 v24, -v0, v15, v8
	v_fmac_f32_e32 v15, v24, v4
	v_fma_f32 v0, -v0, v15, v8
	v_div_fmas_f32 v0, v0, v4, v15
	v_div_fixup_f32 v32, v0, v32, v13
	v_pk_fma_f32 v[34:35], v[14:15], v[38:39], v[34:35] op_sel_hi:[0,1,1]
	v_lshlrev_b32_e32 v13, 16, v25
	v_and_b32_e32 v15, 0xffff0000, v25
	v_pk_mul_f32 v[32:33], v[32:33], v[34:35]
	v_mul_f32_e32 v4, 0xbfb8aa3b, v13
	v_and_b32_e32 v25, 0xffff0000, v1
	v_lshlrev_b32_e32 v8, 16, v1
	v_mul_f32_e32 v1, 0xbfb8aa3b, v15
	v_cvt_pk_bf16_f32 v0, v32, v33
	v_exp_f32_e32 v4, v4
	v_lshlrev_b32_e32 v32, 16, v5
	v_and_b32_e32 v33, 0xffff0000, v5
	v_exp_f32_e32 v5, v1
	v_lshlrev_b32_e32 v24, 16, v9
	v_and_b32_e32 v9, 0xffff0000, v9
	v_pk_mul_f32 v[8:9], v[28:29], v[8:9] op_sel:[1,0] op_sel_hi:[0,1]
	v_pk_add_f32 v[4:5], v[4:5], 1.0 op_sel_hi:[1,0]
	v_pk_fma_f32 v[8:9], v[28:29], v[24:25], v[8:9]
	v_lshlrev_b32_e32 v24, 16, v2
	v_and_b32_e32 v25, 0xffff0000, v10
	v_pk_mul_f32 v[24:25], v[28:29], v[24:25] op_sel:[1,0] op_sel_hi:[0,1]
	v_rcp_f32_e32 v5, v5
	s_nop 0
	v_mul_f32_e32 v5, v15, v5
	v_div_scale_f32 v1, s[0:1], v4, v4, v13
	v_rcp_f32_e32 v15, v1
	s_nop 0
	v_fma_f32 v30, -v1, v15, 1.0
	v_fmac_f32_e32 v15, v30, v15
	v_div_scale_f32 v30, vcc, v13, v4, v13
	v_mul_f32_e32 v34, v30, v15
	v_fma_f32 v35, -v1, v34, v30
	v_fmac_f32_e32 v34, v35, v15
	v_fma_f32 v1, -v1, v34, v30
	v_div_fmas_f32 v1, v1, v15, v34
	v_div_fixup_f32 v4, v1, v4, v13
	v_pk_fma_f32 v[8:9], v[14:15], v[32:33], v[8:9] op_sel_hi:[0,1,1]
	v_pk_mul_f32 v[4:5], v[4:5], v[8:9]
	v_lshlrev_b32_e32 v13, 16, v26
	v_and_b32_e32 v15, 0xffff0000, v26
	v_cvt_pk_bf16_f32 v1, v4, v5
	v_mul_f32_e32 v4, 0xbfb8aa3b, v13
	v_and_b32_e32 v9, 0xffff0000, v2
	v_mul_f32_e32 v2, 0xbfb8aa3b, v15
	v_exp_f32_e32 v4, v4
	v_exp_f32_e32 v5, v2
	v_lshlrev_b32_e32 v32, 16, v6
	v_and_b32_e32 v33, 0xffff0000, v6
	v_lshlrev_b32_e32 v8, 16, v10
	v_pk_add_f32 v[4:5], v[4:5], 1.0 op_sel_hi:[1,0]
	v_pk_fma_f32 v[8:9], v[28:29], v[8:9], v[24:25]
	s_nop 0
	v_rcp_f32_e32 v5, v5
	s_nop 0
	v_mul_f32_e32 v5, v15, v5
	v_div_scale_f32 v2, s[0:1], v4, v4, v13
	v_rcp_f32_e32 v6, v2
	s_nop 0
	v_fma_f32 v10, -v2, v6, 1.0
	v_fmac_f32_e32 v6, v10, v6
	v_div_scale_f32 v10, vcc, v13, v4, v13
	v_mul_f32_e32 v15, v10, v6
	v_fma_f32 v26, -v2, v15, v10
	v_fmac_f32_e32 v15, v26, v6
	v_fma_f32 v2, -v2, v15, v10
	v_div_fmas_f32 v2, v2, v6, v15
	v_div_fixup_f32 v4, v2, v4, v13
	v_pk_fma_f32 v[8:9], v[14:15], v[32:33], v[8:9] op_sel_hi:[0,1,1]
	v_pk_mul_f32 v[4:5], v[4:5], v[8:9]
	v_lshlrev_b32_e32 v13, 16, v27
	v_and_b32_e32 v15, 0xffff0000, v27
	v_cvt_pk_bf16_f32 v2, v4, v5
	v_mul_f32_e32 v4, 0xbfb8aa3b, v13
	v_and_b32_e32 v9, 0xffff0000, v3
	v_lshlrev_b32_e32 v10, 16, v3
	v_mul_f32_e32 v3, 0xbfb8aa3b, v15
	v_exp_f32_e32 v4, v4
	v_exp_f32_e32 v5, v3
	v_lshlrev_b32_e32 v8, 16, v11
	v_and_b32_e32 v11, 0xffff0000, v11
	v_pk_mul_f32 v[10:11], v[28:29], v[10:11] op_sel:[1,0] op_sel_hi:[0,1]
	v_pk_add_f32 v[4:5], v[4:5], 1.0 op_sel_hi:[1,0]
; DI float lo16(unsigned w) { return __uint_as_float(w << 16); }
; DI float hi16(unsigned w) { return __uint_as_float(w & 0xffff0000u); }
; DI float siluf_(float x) { return x / (1.f + __expf(-x)); }
; DI void dilcomb_item(const Params& p, int it) {
;     ...
;     const float l0 = lse[((size_t)0 * T_ + tok) * 4 + h], l1 = lse[((size_t)1 * T_ + tok) * 4 + h], l2 = lse[((size_t)2 * T_ + tok) * 4 + h];
;     const float mx = fmaxf(l0, fmaxf(l1, l2));
;     float w0 = __expf(l0 - mx), w1 = __expf(l1 - mx), w2 = __expf(l2 - mx);
;     const float iw = 1.f / (w0 + w1 + w2); w0 *= iw; w1 *= iw; w2 *= iw;
;     const u32x4 a = *(const u32x4*)(od + ((size_t)0 * T_ + tok) * 256 + c8 * 8), bq = *(const u32x4*)(od + ((size_t)1 * T_ + tok) * 256 + c8 * 8), cq = *(const u32x4*)(od + ((size_t)2 * T_ + tok) * 256 + c8 * 8);
;     const u32x4 z = *(const u32x4*)(proj + tok * NP + C_BZ + c8 * 8);
;     u32x4 r;
; #pragma unroll
;     for (int e = 0; e < 4; ++e) {
;       const float v0 = (w0 * lo16(a[e]) + w1 * lo16(bq[e]) + w2 * lo16(cq[e])) * siluf_(lo16(z[e]));
;       const float v1 = (w0 * hi16(a[e]) + w1 * hi16(bq[e]) + w2 * hi16(cq[e])) * siluf_(hi16(z[e]));
;       r[e] = pk2(v0, v1);
;     }
;     *(u32x4*)(y + tok * 1024 + 256 + c8 * 8) = r;
; __global__ void __launch_bounds__(256, 2) hybrid_megakernel(Params p) {
;     ...
;       for (int k = 0; k < mine; ++k) { const int slot = start + k; sgu_item(p, l, slot * 8 + x, lds); pool_item(p, l, slot * 8 + x, lds); dilcomb_item(p, x * 64 + slot); }
	v_pk_fma_f32 v[8:9], v[28:29], v[8:9], v[10:11]
	v_lshlrev_b32_e32 v6, 16, v7
	v_and_b32_e32 v7, 0xffff0000, v7
	v_pk_fma_f32 v[6:7], v[14:15], v[6:7], v[8:9] op_sel_hi:[0,1,1]
	s_nop 0
	v_rcp_f32_e32 v5, v5
	s_nop 0
	v_mul_f32_e32 v5, v15, v5
	s_nop 0
	v_rcp_f32_e32 v4, v4
	s_nop 0
	v_mul_f32_e32 v4, v13, v4
	v_pk_mul_f32 v[4:5], v[4:5], v[6:7]
	s_nop 0
	v_cvt_pk_bf16_f32 v3, v4, v5
	v_mad_i64_i32 v[4:5], s[0:1], v12, s37, v[22:23]
	v_lshl_add_u64 v[4:5], v[4:5], 0, v[184:185]
	v_add_co_u32_e32 v4, vcc, s74, v4
	s_nop 1
	v_addc_co_u32_e32 v5, vcc, 0, v5, vcc
	global_store_dwordx4 v[4:5], v[0:3], off offset:512
	s_nop 1
	v_add_u32_e32 v0, 0x300, v31
	v_ashrrev_i32_e32 v22, 5, v0
	v_ashrrev_i32_e32 v23, 31, v22
	v_lshl_add_u64 v[0:1], v[22:23], 4, v[18:19]
	v_lshl_add_u64 v[4:5], v[22:23], 0, s[96:97]
	v_mov_b32_e32 v2, v156
	v_lshl_add_u64 v[0:1], v[4:5], 4, v[18:19]
	v_lshl_add_u64 v[6:7], v[22:23], 0, s[4:5]
	v_mov_b32_e32 v3, v157
	v_lshl_add_u64 v[0:1], v[6:7], 4, v[18:19]
	v_mov_b32_e32 v0, v158
	v_lshlrev_b64 v[4:5], 9, v[4:5]
	v_lshl_add_u64 v[4:5], v[16:17], 0, v[4:5]
	v_max3_f32 v1, v2, v3, v0
	v_sub_f32_e32 v2, v2, v1
	v_mul_f32_e32 v2, 0x3fb8aa3b, v2
	v_exp_f32_e32 v25, v2
	v_sub_f32_e32 v2, v3, v1
	v_mul_f32_e32 v2, 0x3fb8aa3b, v2
	v_sub_f32_e32 v0, v0, v1
	v_exp_f32_e32 v24, v2
	v_mul_f32_e32 v0, 0x3fb8aa3b, v0
	v_exp_f32_e32 v0, v0
	v_add_f32_e32 v1, v25, v24
	v_add_f32_e32 v1, v0, v1
	s_nop 0
	v_rcp_f32_e32 v26, v1
	s_nop 0
	v_mul_f32_e32 v18, v0, v26
	v_lshlrev_b64 v[0:1], 9, v[22:23]
	v_lshl_add_u64 v[0:1], v[16:17], 0, v[0:1]
	v_mov_b32_e32 v0, v128
	v_mov_b32_e32 v1, v129
	v_mov_b32_e32 v2, v130
	v_mov_b32_e32 v3, v131
	s_nop 0
	v_mov_b32_e32 v8, v132
	v_mov_b32_e32 v9, v133
	v_mov_b32_e32 v10, v134
	v_mov_b32_e32 v11, v135
	v_lshlrev_b64 v[4:5], 9, v[6:7]
	v_lshl_add_u64 v[4:5], v[16:17], 0, v[4:5]
	v_mad_i64_i32 v[16:17], s[0:1], v22, s33, v[20:21]
	v_lshl_add_u64 v[12:13], v[16:17], 0, v[184:185]
	v_add_co_u32_e32 v12, vcc, s93, v12
	v_mov_b32_e32 v4, v136
	v_mov_b32_e32 v5, v137
	v_mov_b32_e32 v6, v138
	v_mov_b32_e32 v7, v139
	s_nop 0
	v_addc_co_u32_e32 v13, vcc, 0, v13, vcc
	v_mov_b32_e32 v12, v140
	v_mov_b32_e32 v13, v141
	v_mov_b32_e32 v14, v142
	v_mov_b32_e32 v15, v143
	v_pk_mul_f32 v[20:21], v[24:25], v[26:27] op_sel_hi:[1,0]
	v_and_b32_e32 v27, 0xffff0000, v0
	v_lshlrev_b32_e32 v28, 16, v0
	v_lshlrev_b32_e32 v26, 16, v8
	v_and_b32_e32 v29, 0xffff0000, v8
	v_pk_mul_f32 v[28:29], v[20:21], v[28:29] op_sel:[1,0] op_sel_hi:[0,1]
	v_pk_fma_f32 v[26:27], v[20:21], v[26:27], v[28:29]
	v_lshlrev_b32_e32 v30, 16, v4
	v_and_b32_e32 v31, 0xffff0000, v4
	v_lshlrev_b32_e32 v19, 16, v12
	v_and_b32_e32 v12, 0xffff0000, v12
	v_mul_f32_e32 v23, 0xbfb8aa3b, v19
	v_mul_f32_e32 v0, 0xbfb8aa3b, v12
	v_exp_f32_e32 v24, v23
	v_exp_f32_e32 v25, v0
	v_pk_fma_f32 v[26:27], v[18:19], v[30:31], v[26:27] op_sel_hi:[0,1,1]
	v_pk_add_f32 v[24:25], v[24:25], 1.0 op_sel_hi:[1,0]
	s_nop 0
	s_nop 0
	v_rcp_f32_e32 v25, v25
	s_nop 0
	v_mul_f32_e32 v25, v12, v25
	s_nop 0
	v_rcp_f32_e32 v24, v24
	s_nop 0
	v_mul_f32_e32 v24, v19, v24
	v_lshlrev_b32_e32 v19, 16, v13
	v_and_b32_e32 v23, 0xffff0000, v13
	v_pk_mul_f32 v[24:25], v[24:25], v[26:27]
	v_mul_f32_e32 v4, 0xbfb8aa3b, v19
	v_and_b32_e32 v13, 0xffff0000, v1
	v_lshlrev_b32_e32 v8, 16, v1
	v_mul_f32_e32 v1, 0xbfb8aa3b, v23
	v_cvt_pk_bf16_f32 v0, v24, v25
	v_exp_f32_e32 v4, v4
	v_lshlrev_b32_e32 v24, 16, v5
	v_and_b32_e32 v25, 0xffff0000, v5
	v_exp_f32_e32 v5, v1
	v_lshlrev_b32_e32 v12, 16, v9
	v_and_b32_e32 v9, 0xffff0000, v9
	v_pk_mul_f32 v[8:9], v[20:21], v[8:9] op_sel:[1,0] op_sel_hi:[0,1]
	v_pk_add_f32 v[4:5], v[4:5], 1.0 op_sel_hi:[1,0]
	v_pk_fma_f32 v[8:9], v[20:21], v[12:13], v[8:9]
	v_pk_fma_f32 v[8:9], v[18:19], v[24:25], v[8:9] op_sel_hi:[0,1,1]
	v_lshlrev_b32_e32 v12, 16, v2
	v_lshlrev_b32_e32 v24, 16, v6
	v_rcp_f32_e32 v5, v5
	s_nop 0
	v_mul_f32_e32 v5, v23, v5
	v_and_b32_e32 v25, 0xffff0000, v6
	v_and_b32_e32 v13, 0xffff0000, v10
	v_pk_mul_f32 v[12:13], v[20:21], v[12:13] op_sel:[1,0] op_sel_hi:[0,1]
	v_rcp_f32_e32 v4, v4
	s_nop 0
	v_mul_f32_e32 v4, v19, v4
	v_pk_mul_f32 v[4:5], v[4:5], v[8:9]
	v_lshlrev_b32_e32 v19, 16, v14
	v_and_b32_e32 v14, 0xffff0000, v14
	v_cvt_pk_bf16_f32 v1, v4, v5
	v_mul_f32_e32 v4, 0xbfb8aa3b, v19
	v_and_b32_e32 v9, 0xffff0000, v2
	v_mul_f32_e32 v2, 0xbfb8aa3b, v14
	v_exp_f32_e32 v4, v4
	v_exp_f32_e32 v5, v2
	v_lshlrev_b32_e32 v8, 16, v10
	v_pk_fma_f32 v[8:9], v[20:21], v[8:9], v[12:13]
	v_lshlrev_b32_e32 v12, 16, v15
	v_pk_add_f32 v[4:5], v[4:5], 1.0 op_sel_hi:[1,0]
	v_pk_fma_f32 v[8:9], v[18:19], v[24:25], v[8:9] op_sel_hi:[0,1,1]
	v_and_b32_e32 v13, 0xffff0000, v15
	v_rcp_f32_e32 v5, v5
	s_nop 0
	v_mul_f32_e32 v5, v14, v5
	s_nop 0
	v_rcp_f32_e32 v4, v4
	s_nop 0
	v_mul_f32_e32 v4, v19, v4
	v_pk_mul_f32 v[4:5], v[4:5], v[8:9]
	v_and_b32_e32 v9, 0xffff0000, v3
	v_cvt_pk_bf16_f32 v2, v4, v5
	v_mul_f32_e32 v4, 0xbfb8aa3b, v12
	v_lshlrev_b32_e32 v10, 16, v3
	v_mul_f32_e32 v3, 0xbfb8aa3b, v13
	v_exp_f32_e32 v4, v4
	v_exp_f32_e32 v5, v3
	v_lshlrev_b32_e32 v8, 16, v11
	v_and_b32_e32 v11, 0xffff0000, v11
	v_pk_mul_f32 v[10:11], v[20:21], v[10:11] op_sel:[1,0] op_sel_hi:[0,1]
	v_pk_add_f32 v[4:5], v[4:5], 1.0 op_sel_hi:[1,0]
	v_pk_fma_f32 v[8:9], v[20:21], v[8:9], v[10:11]
	v_lshlrev_b32_e32 v6, 16, v7
	v_and_b32_e32 v7, 0xffff0000, v7
	v_pk_fma_f32 v[6:7], v[18:19], v[6:7], v[8:9] op_sel_hi:[0,1,1]
	s_nop 0
	v_rcp_f32_e32 v5, v5
	s_nop 0
	v_mul_f32_e32 v5, v13, v5
	s_nop 0
	v_rcp_f32_e32 v4, v4
	s_nop 0
	v_mul_f32_e32 v4, v12, v4
	v_pk_mul_f32 v[4:5], v[4:5], v[6:7]
	s_nop 0
	v_cvt_pk_bf16_f32 v3, v4, v5
	v_mad_i64_i32 v[4:5], s[0:1], v22, s37, v[16:17]
	v_lshl_add_u64 v[4:5], v[4:5], 0, v[184:185]
	v_add_co_u32_e32 v4, vcc, 0x2a40000, v4
	s_nop 1
	v_addc_co_u32_e32 v5, vcc, 0, v5, vcc
	v_cmp_eq_u32_e32 vcc, s6, v116
	global_store_dwordx4 v[4:5], v[0:3], off offset:512
	s_cbranch_vccz .LBB0_411
	s_branch .LBB0_345
